# k43 + idle-slot weight-quantisation items: three norm-gain loads issued up front with counted waits instead of one at a time with full drains
# speedup vs baseline: 1.0050x; 1.0050x over previous
.LBB0_1197:
	s_mul_hi_u32 s8, s14, 0xba2e8ba3
	s_lshr_b32 s16, s8, 6
	s_lshr_b32 s8, s8, 7
	s_mulk_i32 s8, 0xff50
	s_mul_i32 s9, s16, 0xb00
	s_add_i32 s17, s12, s8
	s_sub_i32 s26, s15, s9
	s_addk_i32 s17, 0xf0
	s_cmpk_lt_u32 s17, 0x58
	s_mov_b64 s[8:9], s[20:21]
	s_cselect_b32 s10, 22, 23
	s_ashr_i32 s11, s10, 31
	s_lshl_b64 s[10:11], s[10:11], 3
	s_add_u32 s10, s0, s10
	s_addc_u32 s11, s1, s11
	s_load_dwordx2 s[22:23], s[10:11], 0x0
	s_mov_b32 s10, 21
	s_ashr_i32 s11, s10, 31
	s_lshl_b64 s[10:11], s[10:11], 3
	s_add_u32 s10, s0, s10
	s_addc_u32 s11, s1, s11
	s_load_dwordx2 s[10:11], s[10:11], 0x0
	s_lshl_b64 s[24:25], s[26:27], 2
	s_waitcnt lgkmcnt(0)
	s_add_u32 s22, s22, s24
	s_addc_u32 s23, s23, s25
	v_lshl_add_u64 v[2:3], s[22:23], 0, v[0:1]
	s_mov_b64 s[22:23], 0xb00000
	v_lshl_add_u64 v[84:85], v[50:51], 2, s[10:11]
	s_mov_b64 s[10:11], 0x1000
	v_lshl_add_u64 v[2:3], v[2:3], 0, s[22:23]
	v_lshl_add_u64 v[104:105], v[84:85], 0, s[10:11]
	v_add_co_u32_e32 v84, vcc, s81, v84
	v_lshl_add_u64 v[4:5], v[2:3], 0, v[52:53]
	s_nop 0
	v_addc_co_u32_e32 v85, vcc, 0, v85, vcc
	global_load_dwordx4 v[86:89], v[4:5], off sc1 nt
	global_load_dwordx4 v[116:119], v[84:85], off sc1
	global_load_dwordx4 v[120:123], v[104:105], off offset:1024 sc1
	global_load_dwordx4 v[124:127], v[104:105], off offset:2048 sc1
	global_load_dwordx4 v[128:131], v[104:105], off offset:3072 sc1
	v_lshl_add_u64 v[4:5], v[2:3], 0, v[54:55]
	global_load_dwordx4 v[94:97], v[4:5], off sc1 nt
	v_lshl_add_u64 v[4:5], v[2:3], 0, v[56:57]
	global_load_dwordx4 v[98:101], v[4:5], off sc1 nt
	v_lshl_add_u64 v[4:5], v[2:3], 0, v[58:59]
	global_load_dwordx4 v[112:115], v[4:5], off sc1 nt
	v_lshl_add_u64 v[4:5], v[2:3], 0, v[60:61]
	global_load_dwordx4 v[46:49], v[4:5], off sc1 nt
	v_lshl_add_u64 v[4:5], v[2:3], 0, v[62:63]
	global_load_dwordx4 v[42:45], v[4:5], off sc1 nt
	v_lshl_add_u64 v[4:5], v[2:3], 0, v[64:65]
	global_load_dwordx4 v[38:41], v[4:5], off sc1 nt
	v_lshl_add_u64 v[4:5], v[2:3], 0, v[66:67]
	global_load_dwordx4 v[34:37], v[4:5], off sc1 nt
	v_lshl_add_u64 v[4:5], v[2:3], 0, v[68:69]
	global_load_dwordx4 v[30:33], v[4:5], off sc1 nt
	v_lshl_add_u64 v[4:5], v[2:3], 0, v[70:71]
	global_load_dwordx4 v[26:29], v[4:5], off sc1 nt
	v_lshl_add_u64 v[4:5], v[2:3], 0, v[72:73]
	global_load_dwordx4 v[22:25], v[4:5], off sc1 nt
	v_lshl_add_u64 v[4:5], v[2:3], 0, v[74:75]
	global_load_dwordx4 v[18:21], v[4:5], off sc1 nt
	v_lshl_add_u64 v[4:5], v[2:3], 0, v[76:77]
	global_load_dwordx4 v[14:17], v[4:5], off sc1 nt
	v_lshl_add_u64 v[4:5], v[2:3], 0, v[78:79]
	global_load_dwordx4 v[10:13], v[4:5], off sc1 nt
	v_lshl_add_u64 v[4:5], v[2:3], 0, v[80:81]
	global_load_dwordx4 v[6:9], v[4:5], off sc1 nt
	v_lshl_add_u64 v[2:3], v[2:3], 0, v[82:83]
	global_load_dwordx4 v[2:5], v[2:3], off sc1 nt
	s_waitcnt vmcnt(15)
	v_pk_mul_f32 v[84:85], v[88:89], v[116:117] op_sel_hi:[1,0]
	v_pk_mul_f32 v[92:93], v[86:87], v[116:117] op_sel_hi:[1,0]
	v_max_f32_e64 v87, |v84|, |v85|
	v_max_f32_e64 v86, |v92|, |v93|
	v_max3_f32 v88, v86, 0, v87
	s_waitcnt vmcnt(14)
	v_pk_mul_f32 v[86:87], v[96:97], v[116:117] op_sel:[0,1]
	v_pk_mul_f32 v[94:95], v[94:95], v[116:117] op_sel:[0,1]
	v_max_f32_e64 v90, |v86|, |v87|
	v_max_f32_e64 v89, |v94|, |v95|
	v_max3_f32 v90, v88, v89, v90
	s_waitcnt vmcnt(13)
	v_pk_mul_f32 v[88:89], v[100:101], v[118:119] op_sel_hi:[1,0]
	v_pk_mul_f32 v[96:97], v[98:99], v[118:119] op_sel_hi:[1,0]
	v_max_f32_e64 v98, |v88|, |v89|
	v_max_f32_e64 v91, |v96|, |v97|
	v_max3_f32 v100, v90, v91, v98
	v_mov_b32_e32 v98, v119
	s_waitcnt vmcnt(12)
	v_pk_mul_f32 v[90:91], v[114:115], v[98:99] op_sel_hi:[1,0]
	v_pk_mul_f32 v[98:99], v[112:113], v[98:99] op_sel_hi:[1,0]
	v_max_f32_e64 v102, |v90|, |v91|
	v_max_f32_e64 v101, |v98|, |v99|
	v_max3_f32 v111, v100, v101, v102
	s_waitcnt vmcnt(8)
	v_mov_b32_e32 v100, v120
	v_mov_b32_e32 v101, v121
	v_mov_b32_e32 v102, v122
	v_mov_b32_e32 v103, v123
	v_pk_mul_f32 v[48:49], v[48:49], v[100:101] op_sel_hi:[1,0]
	v_pk_mul_f32 v[46:47], v[46:47], v[100:101] op_sel_hi:[1,0]
	v_max_f32_e64 v113, |v48|, |v49|
	v_max_f32_e64 v112, |v46|, |v47|
	v_pk_mul_f32 v[44:45], v[44:45], v[100:101] op_sel:[0,1]
	v_pk_mul_f32 v[42:43], v[42:43], v[100:101] op_sel:[0,1]
	v_max3_f32 v111, v111, v112, v113
	v_max_f32_e64 v100, |v42|, |v43|
	v_max_f32_e64 v101, |v44|, |v45|
	v_pk_mul_f32 v[40:41], v[40:41], v[102:103] op_sel_hi:[1,0]
	v_pk_mul_f32 v[38:39], v[38:39], v[102:103] op_sel_hi:[1,0]
	v_max3_f32 v100, v111, v100, v101
	v_max_f32_e64 v101, |v38|, |v39|
	v_max_f32_e64 v102, |v40|, |v41|
	v_max3_f32 v101, v100, v101, v102
	v_mov_b32_e32 v100, v103
	v_pk_mul_f32 v[36:37], v[36:37], v[100:101] op_sel_hi:[1,0]
	v_pk_mul_f32 v[34:35], v[34:35], v[100:101] op_sel_hi:[1,0]
	v_max_f32_e64 v102, |v36|, |v37|
	v_max_f32_e64 v100, |v34|, |v35|
	v_max3_f32 v111, v101, v100, v102
	s_waitcnt vmcnt(4)
	v_mov_b32_e32 v100, v124
	v_mov_b32_e32 v101, v125
	v_mov_b32_e32 v102, v126
	v_mov_b32_e32 v103, v127
	v_pk_mul_f32 v[32:33], v[32:33], v[100:101] op_sel_hi:[1,0]
	v_pk_mul_f32 v[30:31], v[30:31], v[100:101] op_sel_hi:[1,0]
	v_max_f32_e64 v113, |v32|, |v33|
	v_max_f32_e64 v112, |v30|, |v31|
	v_pk_mul_f32 v[28:29], v[28:29], v[100:101] op_sel:[0,1]
	v_pk_mul_f32 v[26:27], v[26:27], v[100:101] op_sel:[0,1]
	v_max3_f32 v111, v111, v112, v113
	v_max_f32_e64 v100, |v26|, |v27|
	v_max_f32_e64 v101, |v28|, |v29|
	v_max3_f32 v111, v111, v100, v101
	v_pk_mul_f32 v[24:25], v[24:25], v[102:103] op_sel_hi:[1,0]
	v_pk_mul_f32 v[100:101], v[22:23], v[102:103] op_sel_hi:[1,0]
	v_max_f32_e64 v23, |v24|, |v25|
	v_max_f32_e64 v22, |v100|, |v101|
	v_mov_b32_e32 v102, v103
	v_max3_f32 v111, v111, v22, v23
	v_pk_mul_f32 v[22:23], v[20:21], v[102:103] op_sel_hi:[1,0]
	v_pk_mul_f32 v[102:103], v[18:19], v[102:103] op_sel_hi:[1,0]
	v_max_f32_e64 v19, |v22|, |v23|
	v_max_f32_e64 v18, |v102|, |v103|
	v_max3_f32 v111, v111, v18, v19
	s_waitcnt vmcnt(0)
	v_mov_b32_e32 v18, v128
	v_mov_b32_e32 v19, v129
	v_mov_b32_e32 v20, v130
	v_mov_b32_e32 v21, v131
	v_pk_mul_f32 v[16:17], v[16:17], v[18:19] op_sel_hi:[1,0]
	v_pk_mul_f32 v[14:15], v[14:15], v[18:19] op_sel_hi:[1,0]
	v_max_f32_e64 v105, |v16|, |v17|
	v_max_f32_e64 v104, |v14|, |v15|
	v_pk_mul_f32 v[12:13], v[12:13], v[18:19] op_sel:[0,1]
	v_pk_mul_f32 v[10:11], v[10:11], v[18:19] op_sel:[0,1]
	v_max3_f32 v104, v111, v104, v105
	v_max_f32_e64 v18, |v10|, |v11|
	v_max_f32_e64 v19, |v12|, |v13|
	v_pk_mul_f32 v[8:9], v[8:9], v[20:21] op_sel_hi:[1,0]
	v_pk_mul_f32 v[6:7], v[6:7], v[20:21] op_sel_hi:[1,0]
	v_max3_f32 v18, v104, v18, v19
	v_max_f32_e64 v19, |v6|, |v7|
	v_max_f32_e64 v20, |v8|, |v9|
	v_max3_f32 v19, v18, v19, v20
	v_mov_b32_e32 v18, v21
	v_pk_mul_f32 v[4:5], v[4:5], v[18:19] op_sel_hi:[1,0]
	v_pk_mul_f32 v[2:3], v[2:3], v[18:19] op_sel_hi:[1,0]
	v_max_f32_e64 v20, |v4|, |v5|
	v_max_f32_e64 v18, |v2|, |v3|
	v_max3_f32 v18, v19, v18, v20
	ds_swizzle_b32 v19, v18 offset:swizzle(SWAP,1)
	s_waitcnt lgkmcnt(0)
	v_max_f32_e32 v19, v19, v19
	v_max_f32_e32 v18, v18, v19
	ds_swizzle_b32 v19, v18 offset:swizzle(SWAP,2)
	s_waitcnt lgkmcnt(0)
	v_max_f32_e32 v19, v19, v19
	v_max_f32_e32 v18, v18, v19
	ds_swizzle_b32 v19, v18 offset:swizzle(SWAP,4)
	s_waitcnt lgkmcnt(0)
	v_max_f32_e32 v19, v19, v19
	v_max_f32_e32 v18, v18, v19
	ds_swizzle_b32 v19, v18 offset:swizzle(SWAP,8)
	s_waitcnt lgkmcnt(0)
	v_max_f32_e32 v19, v19, v19
	v_max_f32_e32 v18, v18, v19
	ds_swizzle_b32 v19, v18 offset:swizzle(SWAP,16)
	s_waitcnt lgkmcnt(0)
	v_max_f32_e32 v19, v19, v19
	v_max_f32_e32 v18, v18, v19
	v_mov_b32_e32 v19, v18
	s_nop 1
	v_permlane32_swap_b32_e32 v18, v19
	s_and_saveexec_b64 s[10:11], s[4:5]
	v_max_f32_e32 v18, v18, v18
	v_max_f32_e32 v19, v19, v19
	v_max_f32_e32 v18, v18, v19
	v_add_u32_e32 v19, 0, v107
	ds_write_b32 v19, v18 offset:33280
	s_or_b64 exec, exec, s[10:11]
	s_waitcnt lgkmcnt(0)
	s_barrier
	ds_read_b128 v[18:21], v1 offset:33280
	ds_read_b128 v[112:115], v1 offset:33296
	s_mulk_i32 s16, 0x1600
	s_sub_i32 s10, s13, s16
	s_and_b32 s10, s10, 0x1f00
	s_waitcnt lgkmcnt(1)
	v_max_f32_e32 v19, v19, v19
	v_max_f32_e32 v18, v18, v18
	v_max_f32_e32 v18, v18, v19
	v_max_f32_e32 v19, v21, v21
	v_max_f32_e32 v20, v20, v20
	v_max_f32_e32 v19, v20, v19
	s_waitcnt lgkmcnt(0)
	v_max_f32_e32 v20, v115, v115
	v_max_f32_e32 v21, v114, v114
	v_max_f32_e32 v20, v21, v20
	s_cmpk_gt_u32 s17, 0x57
	v_max3_f32 v20, v112, v113, v20
	s_cselect_b32 s11, 0x80, 0
	v_max3_f32 v18, v18, v19, v20
	s_or_b32 s16, s10, s11
	v_div_scale_f32 v19, s[10:11], v18, v18, s34
	v_rcp_f32_e32 v20, v19
	s_and_b32 s17, s26, 0x60
	s_or_b32 s22, s16, s17
	s_add_u32 s16, s8, 0x4200000
	v_fma_f32 v21, -v19, v20, 1.0
	v_fmac_f32_e32 v20, v21, v20
	v_div_scale_f32 v21, vcc, s34, v18, s34
	v_mul_f32_e32 v104, v21, v20
	v_fma_f32 v105, -v19, v104, v21
	v_fmac_f32_e32 v104, v105, v20
	v_fma_f32 v19, -v19, v104, v21
	v_div_fmas_f32 v19, v19, v20, v104
	v_div_fixup_f32 v19, v19, v18, s34
	v_cmp_lt_f32_e32 vcc, 0, v18
	s_addc_u32 s10, s9, 0
	s_and_b32 s17, s10, 0xffff
	v_cndmask_b32_e32 v19, 0, v19, vcc
	v_mul_f32_e32 v21, v94, v19
	v_mul_f32_e32 v42, v42, v19
	v_mul_f32_e32 v20, v92, v19
	v_mul_f32_e32 v92, v96, v19
	v_mul_f32_e32 v94, v98, v19
	v_rndne_f32_e32 v21, v21
	v_mul_f32_e32 v46, v46, v19
	v_mul_f32_e32 v38, v38, v19
	v_mul_f32_e32 v34, v34, v19
	v_rndne_f32_e32 v42, v42
	v_rndne_f32_e32 v20, v20
	v_cvt_i32_f32_e32 v21, v21
	v_rndne_f32_e32 v92, v92
	v_rndne_f32_e32 v94, v94
	v_rndne_f32_e32 v46, v46
	v_cvt_i32_f32_e32 v42, v42
	v_rndne_f32_e32 v38, v38
	v_rndne_f32_e32 v34, v34
	v_cvt_i32_f32_e32 v20, v20
	v_cvt_i32_f32_sdwa v92, v92 dst_sel:WORD_1 dst_unused:UNUSED_PAD src0_sel:DWORD
	v_cvt_i32_f32_e32 v94, v94
	v_cvt_i32_f32_e32 v46, v46
	v_cvt_i32_f32_sdwa v38, v38 dst_sel:WORD_1 dst_unused:UNUSED_PAD src0_sel:DWORD
	v_cvt_i32_f32_e32 v34, v34
	v_lshlrev_b32_e32 v21, 8, v21
	v_lshlrev_b32_e32 v42, 8, v42
	v_and_b32_e32 v21, 0xff00, v21
	v_and_b32_e32 v92, 0xff0000, v92
	v_perm_b32 v20, v94, v20, s35
	v_and_b32_e32 v42, 0xff00, v42
	v_and_b32_e32 v38, 0xff0000, v38
	v_perm_b32 v34, v34, v46, s35
	v_or3_b32 v20, v20, v21, v92
	v_or3_b32 v34, v34, v42, v38
	v_mul_f32_e32 v92, v95, v19
	ds_write2st64_b32 v109, v20, v34 offset1:1
	v_mul_f32_e32 v34, v43, v19
	v_mul_f32_e32 v21, v93, v19
	v_mul_f32_e32 v93, v97, v19
	v_mul_f32_e32 v94, v99, v19
	v_rndne_f32_e32 v92, v92
	v_mul_f32_e32 v20, v47, v19
	v_mul_f32_e32 v38, v39, v19
	v_mul_f32_e32 v35, v35, v19
	v_rndne_f32_e32 v34, v34
	v_rndne_f32_e32 v21, v21
	v_cvt_i32_f32_e32 v92, v92
	v_rndne_f32_e32 v93, v93
	v_rndne_f32_e32 v94, v94
	v_rndne_f32_e32 v20, v20
	v_cvt_i32_f32_e32 v34, v34
	v_rndne_f32_e32 v38, v38
	v_rndne_f32_e32 v35, v35
	v_cvt_i32_f32_e32 v21, v21
	v_cvt_i32_f32_sdwa v93, v93 dst_sel:WORD_1 dst_unused:UNUSED_PAD src0_sel:DWORD
	v_cvt_i32_f32_e32 v94, v94
	v_cvt_i32_f32_e32 v20, v20
	v_cvt_i32_f32_sdwa v38, v38 dst_sel:WORD_1 dst_unused:UNUSED_PAD src0_sel:DWORD
	v_cvt_i32_f32_e32 v35, v35
	v_lshlrev_b32_e32 v92, 8, v92
	v_lshlrev_b32_e32 v34, 8, v34
	v_and_b32_e32 v92, 0xff00, v92
	v_and_b32_e32 v93, 0xff0000, v93
	v_perm_b32 v21, v94, v21, s35
	v_and_b32_e32 v34, 0xff00, v34
	v_and_b32_e32 v38, 0xff0000, v38
	v_perm_b32 v20, v35, v20, s35
	v_or3_b32 v21, v21, v92, v93
	v_or3_b32 v20, v20, v34, v38
	v_add_u32_e32 v34, 16, v109
	v_mul_f32_e32 v86, v86, v19
	ds_write2st64_b32 v34, v21, v20 offset0:4 offset1:5
	v_mul_f32_e32 v21, v44, v19
	v_mul_f32_e32 v84, v84, v19
	v_mul_f32_e32 v88, v88, v19
	v_mul_f32_e32 v90, v90, v19
	v_rndne_f32_e32 v86, v86
	v_mul_f32_e32 v20, v48, v19
	v_mul_f32_e32 v35, v40, v19
	v_mul_f32_e32 v36, v36, v19
	v_rndne_f32_e32 v21, v21
	v_rndne_f32_e32 v84, v84
	v_cvt_i32_f32_e32 v86, v86
	v_rndne_f32_e32 v88, v88
	v_rndne_f32_e32 v90, v90
	v_rndne_f32_e32 v20, v20
	v_cvt_i32_f32_e32 v21, v21
	v_rndne_f32_e32 v35, v35
	v_rndne_f32_e32 v36, v36
	v_cvt_i32_f32_e32 v84, v84
	v_cvt_i32_f32_sdwa v88, v88 dst_sel:WORD_1 dst_unused:UNUSED_PAD src0_sel:DWORD
	v_cvt_i32_f32_e32 v90, v90
	v_cvt_i32_f32_e32 v20, v20
	v_cvt_i32_f32_sdwa v35, v35 dst_sel:WORD_1 dst_unused:UNUSED_PAD src0_sel:DWORD
	v_cvt_i32_f32_e32 v36, v36
	v_lshlrev_b32_e32 v86, 8, v86
	v_lshlrev_b32_e32 v21, 8, v21
	v_and_b32_e32 v86, 0xff00, v86
	v_and_b32_e32 v88, 0xff0000, v88
	v_perm_b32 v84, v90, v84, s35
	v_and_b32_e32 v21, 0xff00, v21
	v_and_b32_e32 v35, 0xff0000, v35
	v_perm_b32 v20, v36, v20, s35
	v_or3_b32 v84, v84, v86, v88
	v_mul_f32_e32 v86, v87, v19
	v_or3_b32 v20, v20, v21, v35
	v_add_u32_e32 v21, 32, v109
	v_mul_f32_e32 v35, v45, v19
	v_mul_f32_e32 v85, v85, v19
	v_mul_f32_e32 v87, v89, v19
	v_mul_f32_e32 v88, v91, v19
	v_rndne_f32_e32 v86, v86
	ds_write2st64_b32 v21, v84, v20 offset0:8 offset1:9
	v_mul_f32_e32 v20, v49, v19
	v_mul_f32_e32 v36, v41, v19
	v_mul_f32_e32 v37, v37, v19
	v_rndne_f32_e32 v35, v35
	v_rndne_f32_e32 v85, v85
	v_cvt_i32_f32_e32 v86, v86
	v_rndne_f32_e32 v87, v87
	v_rndne_f32_e32 v88, v88
	v_rndne_f32_e32 v20, v20
	v_cvt_i32_f32_e32 v35, v35
	v_rndne_f32_e32 v36, v36
	v_rndne_f32_e32 v37, v37
	v_cvt_i32_f32_e32 v85, v85
	v_cvt_i32_f32_sdwa v87, v87 dst_sel:WORD_1 dst_unused:UNUSED_PAD src0_sel:DWORD
	v_cvt_i32_f32_e32 v88, v88
	v_cvt_i32_f32_e32 v20, v20
	v_cvt_i32_f32_sdwa v36, v36 dst_sel:WORD_1 dst_unused:UNUSED_PAD src0_sel:DWORD
	v_cvt_i32_f32_e32 v37, v37
	v_lshlrev_b32_e32 v86, 8, v86
	v_lshlrev_b32_e32 v35, 8, v35
	v_and_b32_e32 v86, 0xff00, v86
	v_and_b32_e32 v87, 0xff0000, v87
	v_perm_b32 v85, v88, v85, s35
	v_and_b32_e32 v35, 0xff00, v35
	v_and_b32_e32 v36, 0xff0000, v36
	v_perm_b32 v20, v37, v20, s35
	v_or3_b32 v85, v85, v86, v87
	v_or3_b32 v20, v20, v35, v36
	v_add_u32_e32 v35, 48, v109
	v_mul_f32_e32 v26, v26, v19
	v_mul_f32_e32 v10, v10, v19
	ds_write2st64_b32 v35, v85, v20 offset0:12 offset1:13
	v_mul_f32_e32 v20, v30, v19
	v_mul_f32_e32 v30, v100, v19
	v_mul_f32_e32 v36, v102, v19
	v_rndne_f32_e32 v26, v26
	v_mul_f32_e32 v14, v14, v19
	v_mul_f32_e32 v6, v6, v19
	v_mul_f32_e32 v2, v2, v19
	v_rndne_f32_e32 v10, v10
	v_rndne_f32_e32 v20, v20
	v_cvt_i32_f32_e32 v26, v26
	v_rndne_f32_e32 v30, v30
	v_rndne_f32_e32 v36, v36
	v_rndne_f32_e32 v14, v14
	v_cvt_i32_f32_e32 v10, v10
	v_rndne_f32_e32 v6, v6
	v_rndne_f32_e32 v2, v2
	v_cvt_i32_f32_e32 v20, v20
	v_cvt_i32_f32_sdwa v30, v30 dst_sel:WORD_1 dst_unused:UNUSED_PAD src0_sel:DWORD
	v_cvt_i32_f32_e32 v36, v36
	v_cvt_i32_f32_e32 v14, v14
	v_cvt_i32_f32_sdwa v6, v6 dst_sel:WORD_1 dst_unused:UNUSED_PAD src0_sel:DWORD
	v_cvt_i32_f32_e32 v2, v2
	v_lshlrev_b32_e32 v26, 8, v26
	v_lshlrev_b32_e32 v10, 8, v10
	v_and_b32_e32 v26, 0xff00, v26
	v_and_b32_e32 v30, 0xff0000, v30
	v_perm_b32 v20, v36, v20, s35
	v_and_b32_e32 v10, 0xff00, v10
	v_and_b32_e32 v6, 0xff0000, v6
	v_perm_b32 v2, v2, v14, s35
	v_or3_b32 v20, v20, v26, v30
	v_mul_f32_e32 v27, v27, v19
	v_or3_b32 v2, v2, v10, v6
	v_mul_f32_e32 v6, v11, v19
	v_mul_f32_e32 v26, v31, v19
	v_mul_f32_e32 v30, v101, v19
	v_mul_f32_e32 v31, v103, v19
	v_rndne_f32_e32 v27, v27
	ds_write2st64_b32 v109, v20, v2 offset0:2 offset1:3
	v_mul_f32_e32 v2, v15, v19
	v_mul_f32_e32 v7, v7, v19
	v_mul_f32_e32 v3, v3, v19
	v_rndne_f32_e32 v6, v6
	v_rndne_f32_e32 v26, v26
	v_cvt_i32_f32_e32 v27, v27
	v_rndne_f32_e32 v30, v30
	v_rndne_f32_e32 v31, v31
	v_rndne_f32_e32 v2, v2
	v_cvt_i32_f32_e32 v6, v6
	v_rndne_f32_e32 v7, v7
	v_rndne_f32_e32 v3, v3
	v_cvt_i32_f32_e32 v26, v26
	v_cvt_i32_f32_sdwa v30, v30 dst_sel:WORD_1 dst_unused:UNUSED_PAD src0_sel:DWORD
	v_cvt_i32_f32_e32 v31, v31
	v_cvt_i32_f32_e32 v2, v2
	v_cvt_i32_f32_sdwa v7, v7 dst_sel:WORD_1 dst_unused:UNUSED_PAD src0_sel:DWORD
	v_cvt_i32_f32_e32 v3, v3
	v_lshlrev_b32_e32 v27, 8, v27
	v_lshlrev_b32_e32 v6, 8, v6
	v_and_b32_e32 v27, 0xff00, v27
	v_and_b32_e32 v30, 0xff0000, v30
	v_perm_b32 v26, v31, v26, s35
	v_and_b32_e32 v6, 0xff00, v6
	v_and_b32_e32 v7, 0xff0000, v7
	v_perm_b32 v2, v3, v2, s35
	v_or3_b32 v26, v26, v27, v30
	v_mul_f32_e32 v28, v28, v19
	v_or3_b32 v2, v2, v6, v7
	v_mul_f32_e32 v3, v12, v19
	v_mul_f32_e32 v27, v32, v19
	v_mul_f32_e32 v24, v24, v19
	v_mul_f32_e32 v22, v22, v19
	v_rndne_f32_e32 v28, v28
	ds_write2st64_b32 v34, v26, v2 offset0:6 offset1:7
	v_mul_f32_e32 v2, v16, v19
	v_mul_f32_e32 v6, v8, v19
	v_mul_f32_e32 v4, v4, v19
	v_rndne_f32_e32 v3, v3
	v_rndne_f32_e32 v27, v27
	v_cvt_i32_f32_e32 v28, v28
	v_rndne_f32_e32 v24, v24
	v_rndne_f32_e32 v22, v22
	v_rndne_f32_e32 v2, v2
	v_cvt_i32_f32_e32 v3, v3
	v_rndne_f32_e32 v6, v6
	v_rndne_f32_e32 v4, v4
	v_cvt_i32_f32_e32 v27, v27
	v_cvt_i32_f32_sdwa v24, v24 dst_sel:WORD_1 dst_unused:UNUSED_PAD src0_sel:DWORD
	v_cvt_i32_f32_e32 v22, v22
	v_cvt_i32_f32_e32 v2, v2
	v_cvt_i32_f32_sdwa v6, v6 dst_sel:WORD_1 dst_unused:UNUSED_PAD src0_sel:DWORD
	v_cvt_i32_f32_e32 v4, v4
	v_lshlrev_b32_e32 v28, 8, v28
	v_lshlrev_b32_e32 v3, 8, v3
	v_and_b32_e32 v28, 0xff00, v28
	v_and_b32_e32 v24, 0xff0000, v24
	v_perm_b32 v22, v22, v27, s35
	v_and_b32_e32 v3, 0xff00, v3
	v_and_b32_e32 v6, 0xff0000, v6
	v_perm_b32 v2, v4, v2, s35
	v_or3_b32 v22, v22, v28, v24
	v_mul_f32_e32 v27, v29, v19
	v_or3_b32 v2, v2, v3, v6
	v_mul_f32_e32 v3, v13, v19
	v_mul_f32_e32 v24, v33, v19
	v_mul_f32_e32 v25, v25, v19
	v_mul_f32_e32 v23, v23, v19
	v_rndne_f32_e32 v27, v27
	ds_write2st64_b32 v21, v22, v2 offset0:10 offset1:11
	v_mul_f32_e32 v2, v17, v19
	v_mul_f32_e32 v4, v9, v19
	v_mul_f32_e32 v5, v5, v19
	v_rndne_f32_e32 v3, v3
	v_rndne_f32_e32 v24, v24
	v_cvt_i32_f32_e32 v27, v27
	v_rndne_f32_e32 v25, v25
	v_rndne_f32_e32 v23, v23
	v_rndne_f32_e32 v2, v2
	v_cvt_i32_f32_e32 v3, v3
	v_rndne_f32_e32 v4, v4
	v_rndne_f32_e32 v5, v5
	v_cvt_i32_f32_e32 v24, v24
	v_cvt_i32_f32_sdwa v25, v25 dst_sel:WORD_1 dst_unused:UNUSED_PAD src0_sel:DWORD
	v_cvt_i32_f32_e32 v23, v23
	v_cvt_i32_f32_e32 v2, v2
	v_cvt_i32_f32_sdwa v4, v4 dst_sel:WORD_1 dst_unused:UNUSED_PAD src0_sel:DWORD
	v_cvt_i32_f32_e32 v5, v5
	v_lshlrev_b32_e32 v27, 8, v27
	v_lshlrev_b32_e32 v3, 8, v3
	v_and_b32_e32 v27, 0xff00, v27
	v_and_b32_e32 v25, 0xff0000, v25
	v_perm_b32 v23, v23, v24, s35
	v_and_b32_e32 v3, 0xff00, v3
	v_and_b32_e32 v4, 0xff0000, v4
	v_perm_b32 v2, v5, v2, s35
	v_or3_b32 v23, v23, v27, v25
	v_or3_b32 v2, v2, v3, v4
	ds_write2st64_b32 v35, v23, v2 offset0:14 offset1:15
	s_waitcnt lgkmcnt(0)
	s_barrier
	ds_read_b128 v[2:5], v110
	ds_read_b128 v[6:9], v110 offset:256
	ds_read_b128 v[10:13], v110 offset:512
	ds_read_b128 v[14:17], v110 offset:768
	v_add_u32_e32 v19, s22, v107
	v_lshl_or_b32 v19, v19, 10, v108
	s_waitcnt lgkmcnt(3)
	buffer_store_dwordx4 v[2:5], v19, s[16:19], 0 offen sc1
	s_waitcnt lgkmcnt(2)
	buffer_store_dwordx4 v[6:9], v19, s[16:19], 0 offen offset:256 sc1
	s_waitcnt lgkmcnt(1)
	buffer_store_dwordx4 v[10:13], v19, s[16:19], 0 offen offset:512 sc1
	s_waitcnt lgkmcnt(0)
	buffer_store_dwordx4 v[14:17], v19, s[16:19], 0 offen offset:768 sc1
	s_and_saveexec_b64 s[10:11], s[6:7]
	s_cbranch_execz .LBB0_1196
	s_lshr_b32 s16, s22, 3
	s_add_u32 s8, s8, s16
	v_mul_f32_e32 v2, 0x3c010204, v18
	s_addc_u32 s9, s9, 0
	v_cndmask_b32_e32 v2, 1.0, v2, vcc
	global_store_dword v237, v2, s[8:9] offset:2112 sc1
	s_branch .LBB0_1196

.LBB0_1208:
	s_mul_hi_u32 s8, s14, 0xba2e8ba3
	s_lshr_b32 s16, s8, 6
	s_lshr_b32 s8, s8, 7
	s_mulk_i32 s8, 0xff50
	s_mul_i32 s9, s16, 0xb00
	s_add_i32 s17, s12, s8
	s_sub_i32 s26, s15, s9
	s_addk_i32 s17, 0xf0
	s_cmpk_lt_u32 s17, 0x58
	s_mov_b64 s[8:9], s[20:21]
	s_cselect_b32 s10, 22, 23
	s_ashr_i32 s11, s10, 31
	s_lshl_b64 s[10:11], s[10:11], 3
	s_add_u32 s10, s0, s10
	s_addc_u32 s11, s1, s11
	s_load_dwordx2 s[22:23], s[10:11], 0x0
	s_mov_b32 s10, 21
	s_ashr_i32 s11, s10, 31
	s_lshl_b64 s[10:11], s[10:11], 3
	s_add_u32 s10, s0, s10
	s_addc_u32 s11, s1, s11
	s_load_dwordx2 s[10:11], s[10:11], 0x0
	s_lshl_b64 s[24:25], s[26:27], 2
	s_waitcnt lgkmcnt(0)
	s_add_u32 s22, s22, s24
	s_addc_u32 s23, s23, s25
	v_lshl_add_u64 v[2:3], s[22:23], 0, v[0:1]
	v_lshl_add_u64 v[4:5], v[2:3], 0, v[52:53]
	v_lshl_add_u64 v[104:105], v[50:51], 2, s[10:11]
	global_load_dwordx4 v[86:89], v[4:5], off sc1 nt
	global_load_dwordx4 v[114:117], v[104:105], off sc1
	global_load_dwordx4 v[120:123], v[104:105], off offset:1024 sc1
	global_load_dwordx4 v[124:127], v[104:105], off offset:2048 sc1
	global_load_dwordx4 v[128:131], v[104:105], off offset:3072 sc1
	v_lshl_add_u64 v[4:5], v[2:3], 0, v[54:55]
	global_load_dwordx4 v[94:97], v[4:5], off sc1 nt
	v_lshl_add_u64 v[4:5], v[2:3], 0, v[56:57]
	global_load_dwordx4 v[98:101], v[4:5], off sc1 nt
	v_lshl_add_u64 v[4:5], v[2:3], 0, v[58:59]
	global_load_dwordx4 v[110:113], v[4:5], off sc1 nt
	v_lshl_add_u64 v[4:5], v[2:3], 0, v[60:61]
	global_load_dwordx4 v[46:49], v[4:5], off sc1 nt
	v_lshl_add_u64 v[4:5], v[2:3], 0, v[62:63]
	global_load_dwordx4 v[42:45], v[4:5], off sc1 nt
	v_lshl_add_u64 v[4:5], v[2:3], 0, v[64:65]
	global_load_dwordx4 v[38:41], v[4:5], off sc1 nt
	v_lshl_add_u64 v[4:5], v[2:3], 0, v[66:67]
	global_load_dwordx4 v[34:37], v[4:5], off sc1 nt
	v_lshl_add_u64 v[4:5], v[2:3], 0, v[68:69]
	global_load_dwordx4 v[30:33], v[4:5], off sc1 nt
	v_lshl_add_u64 v[4:5], v[2:3], 0, v[70:71]
	global_load_dwordx4 v[26:29], v[4:5], off sc1 nt
	v_lshl_add_u64 v[4:5], v[2:3], 0, v[72:73]
	global_load_dwordx4 v[22:25], v[4:5], off sc1 nt
	v_lshl_add_u64 v[4:5], v[2:3], 0, v[74:75]
	global_load_dwordx4 v[18:21], v[4:5], off sc1 nt
	v_lshl_add_u64 v[4:5], v[2:3], 0, v[76:77]
	global_load_dwordx4 v[14:17], v[4:5], off sc1 nt
	v_lshl_add_u64 v[4:5], v[2:3], 0, v[78:79]
	global_load_dwordx4 v[10:13], v[4:5], off sc1 nt
	v_lshl_add_u64 v[4:5], v[2:3], 0, v[80:81]
	global_load_dwordx4 v[6:9], v[4:5], off sc1 nt
	v_lshl_add_u64 v[2:3], v[2:3], 0, v[82:83]
	global_load_dwordx4 v[2:5], v[2:3], off sc1 nt
	s_waitcnt vmcnt(15)
	v_pk_mul_f32 v[84:85], v[88:89], v[114:115] op_sel_hi:[1,0]
	v_pk_mul_f32 v[92:93], v[86:87], v[114:115] op_sel_hi:[1,0]
	v_max_f32_e64 v87, |v84|, |v85|
	v_max_f32_e64 v86, |v92|, |v93|
	v_max3_f32 v88, v86, 0, v87
	s_waitcnt vmcnt(14)
	v_pk_mul_f32 v[86:87], v[96:97], v[114:115] op_sel:[0,1]
	v_pk_mul_f32 v[94:95], v[94:95], v[114:115] op_sel:[0,1]
	v_max_f32_e64 v90, |v86|, |v87|
	v_max_f32_e64 v89, |v94|, |v95|
	v_max3_f32 v90, v88, v89, v90
	s_waitcnt vmcnt(13)
	v_pk_mul_f32 v[88:89], v[100:101], v[116:117] op_sel_hi:[1,0]
	v_pk_mul_f32 v[96:97], v[98:99], v[116:117] op_sel_hi:[1,0]
	v_max_f32_e64 v98, |v88|, |v89|
	v_max_f32_e64 v91, |v96|, |v97|
	v_max3_f32 v100, v90, v91, v98
	v_mov_b32_e32 v98, v117
	s_waitcnt vmcnt(12)
	v_pk_mul_f32 v[90:91], v[112:113], v[98:99] op_sel_hi:[1,0]
	v_pk_mul_f32 v[98:99], v[110:111], v[98:99] op_sel_hi:[1,0]
	v_max_f32_e64 v102, |v90|, |v91|
	v_max_f32_e64 v101, |v98|, |v99|
	v_max3_f32 v110, v100, v101, v102
	s_waitcnt vmcnt(8)
	v_mov_b32_e32 v100, v120
	v_mov_b32_e32 v101, v121
	v_mov_b32_e32 v102, v122
	v_mov_b32_e32 v103, v123
	v_pk_mul_f32 v[48:49], v[48:49], v[100:101] op_sel_hi:[1,0]
	v_pk_mul_f32 v[46:47], v[46:47], v[100:101] op_sel_hi:[1,0]
	v_max_f32_e64 v112, |v48|, |v49|
	v_max_f32_e64 v111, |v46|, |v47|
	v_pk_mul_f32 v[44:45], v[44:45], v[100:101] op_sel:[0,1]
	v_pk_mul_f32 v[42:43], v[42:43], v[100:101] op_sel:[0,1]
	v_max3_f32 v110, v110, v111, v112
	v_max_f32_e64 v100, |v42|, |v43|
	v_max_f32_e64 v101, |v44|, |v45|
	v_pk_mul_f32 v[40:41], v[40:41], v[102:103] op_sel_hi:[1,0]
	v_pk_mul_f32 v[38:39], v[38:39], v[102:103] op_sel_hi:[1,0]
	v_max3_f32 v100, v110, v100, v101
	v_max_f32_e64 v101, |v38|, |v39|
	v_max_f32_e64 v102, |v40|, |v41|
	v_max3_f32 v101, v100, v101, v102
	v_mov_b32_e32 v100, v103
	v_pk_mul_f32 v[36:37], v[36:37], v[100:101] op_sel_hi:[1,0]
	v_pk_mul_f32 v[34:35], v[34:35], v[100:101] op_sel_hi:[1,0]
	v_max_f32_e64 v102, |v36|, |v37|
	v_max_f32_e64 v100, |v34|, |v35|
	v_max3_f32 v110, v101, v100, v102
	s_waitcnt vmcnt(4)
	v_mov_b32_e32 v100, v124
	v_mov_b32_e32 v101, v125
	v_mov_b32_e32 v102, v126
	v_mov_b32_e32 v103, v127
	v_pk_mul_f32 v[32:33], v[32:33], v[100:101] op_sel_hi:[1,0]
	v_pk_mul_f32 v[30:31], v[30:31], v[100:101] op_sel_hi:[1,0]
	v_max_f32_e64 v112, |v32|, |v33|
	v_max_f32_e64 v111, |v30|, |v31|
	v_pk_mul_f32 v[28:29], v[28:29], v[100:101] op_sel:[0,1]
	v_pk_mul_f32 v[26:27], v[26:27], v[100:101] op_sel:[0,1]
	v_max3_f32 v110, v110, v111, v112
	v_max_f32_e64 v100, |v26|, |v27|
	v_max_f32_e64 v101, |v28|, |v29|
	v_max3_f32 v110, v110, v100, v101
	v_pk_mul_f32 v[24:25], v[24:25], v[102:103] op_sel_hi:[1,0]
	v_pk_mul_f32 v[100:101], v[22:23], v[102:103] op_sel_hi:[1,0]
	v_max_f32_e64 v23, |v24|, |v25|
	v_max_f32_e64 v22, |v100|, |v101|
	v_mov_b32_e32 v102, v103
	v_max3_f32 v110, v110, v22, v23
	v_pk_mul_f32 v[22:23], v[20:21], v[102:103] op_sel_hi:[1,0]
	v_pk_mul_f32 v[102:103], v[18:19], v[102:103] op_sel_hi:[1,0]
	v_max_f32_e64 v19, |v22|, |v23|
	v_max_f32_e64 v18, |v102|, |v103|
	v_max3_f32 v110, v110, v18, v19
	s_waitcnt vmcnt(0)
	v_mov_b32_e32 v18, v128
	v_mov_b32_e32 v19, v129
	v_mov_b32_e32 v20, v130
	v_mov_b32_e32 v21, v131
	v_pk_mul_f32 v[16:17], v[16:17], v[18:19] op_sel_hi:[1,0]
	v_pk_mul_f32 v[14:15], v[14:15], v[18:19] op_sel_hi:[1,0]
	v_max_f32_e64 v105, |v16|, |v17|
	v_max_f32_e64 v104, |v14|, |v15|
	v_pk_mul_f32 v[12:13], v[12:13], v[18:19] op_sel:[0,1]
	v_pk_mul_f32 v[10:11], v[10:11], v[18:19] op_sel:[0,1]
	v_max3_f32 v104, v110, v104, v105
	v_max_f32_e64 v18, |v10|, |v11|
	v_max_f32_e64 v19, |v12|, |v13|
	v_pk_mul_f32 v[8:9], v[8:9], v[20:21] op_sel_hi:[1,0]
	v_pk_mul_f32 v[6:7], v[6:7], v[20:21] op_sel_hi:[1,0]
	v_max3_f32 v18, v104, v18, v19
	v_max_f32_e64 v19, |v6|, |v7|
	v_max_f32_e64 v20, |v8|, |v9|
	v_max3_f32 v19, v18, v19, v20
	v_mov_b32_e32 v18, v21
	v_pk_mul_f32 v[4:5], v[4:5], v[18:19] op_sel_hi:[1,0]
	v_pk_mul_f32 v[2:3], v[2:3], v[18:19] op_sel_hi:[1,0]
	v_max_f32_e64 v20, |v4|, |v5|
	v_max_f32_e64 v18, |v2|, |v3|
	v_max3_f32 v18, v19, v18, v20
	ds_swizzle_b32 v19, v18 offset:swizzle(SWAP,1)
	s_waitcnt lgkmcnt(0)
	v_max_f32_e32 v19, v19, v19
	v_max_f32_e32 v18, v18, v19
	ds_swizzle_b32 v19, v18 offset:swizzle(SWAP,2)
	s_waitcnt lgkmcnt(0)
	v_max_f32_e32 v19, v19, v19
	v_max_f32_e32 v18, v18, v19
	ds_swizzle_b32 v19, v18 offset:swizzle(SWAP,4)
	s_waitcnt lgkmcnt(0)
	v_max_f32_e32 v19, v19, v19
	v_max_f32_e32 v18, v18, v19
	ds_swizzle_b32 v19, v18 offset:swizzle(SWAP,8)
	s_waitcnt lgkmcnt(0)
	v_max_f32_e32 v19, v19, v19
	v_max_f32_e32 v18, v18, v19
	ds_swizzle_b32 v19, v18 offset:swizzle(SWAP,16)
	s_waitcnt lgkmcnt(0)
	v_max_f32_e32 v19, v19, v19
	v_max_f32_e32 v18, v18, v19
	v_mov_b32_e32 v19, v18
	s_nop 1
	v_permlane32_swap_b32_e32 v18, v19
	s_and_saveexec_b64 s[10:11], s[2:3]
	v_max_f32_e32 v18, v18, v18
	v_max_f32_e32 v19, v19, v19
	v_max_f32_e32 v18, v18, v19
	v_add_u32_e32 v19, 0, v107
	ds_write_b32 v19, v18 offset:33280
	s_or_b64 exec, exec, s[10:11]
	s_waitcnt lgkmcnt(0)
	s_barrier
	ds_read_b128 v[18:21], v1 offset:33280
	ds_read_b128 v[110:113], v1 offset:33296
	s_mulk_i32 s16, 0x1600
	s_sub_i32 s10, s13, s16
	s_and_b32 s10, s10, 0x1f00
	s_waitcnt lgkmcnt(1)
	v_max_f32_e32 v19, v19, v19
	v_max_f32_e32 v18, v18, v18
	v_max_f32_e32 v18, v18, v19
	v_max_f32_e32 v19, v21, v21
	v_max_f32_e32 v20, v20, v20
	v_max_f32_e32 v19, v20, v19
	s_waitcnt lgkmcnt(0)
	v_max_f32_e32 v20, v113, v113
	v_max_f32_e32 v21, v112, v112
	v_max_f32_e32 v20, v21, v20
	s_cmpk_gt_u32 s17, 0x57
	v_max3_f32 v20, v110, v111, v20
	s_cselect_b32 s11, 0x80, 0
	v_max3_f32 v18, v18, v19, v20
	s_or_b32 s16, s10, s11
	v_div_scale_f32 v19, s[10:11], v18, v18, s34
	v_rcp_f32_e32 v20, v19
	s_and_b32 s17, s26, 0x60
	s_or_b32 s22, s16, s17
	s_add_u32 s16, s8, 0x1c80000
	v_fma_f32 v21, -v19, v20, 1.0
	v_fmac_f32_e32 v20, v21, v20
	v_div_scale_f32 v21, vcc, s34, v18, s34
	v_mul_f32_e32 v104, v21, v20
	v_fma_f32 v105, -v19, v104, v21
	v_fmac_f32_e32 v104, v105, v20
	v_fma_f32 v19, -v19, v104, v21
	v_div_fmas_f32 v19, v19, v20, v104
	v_div_fixup_f32 v19, v19, v18, s34
	v_cmp_lt_f32_e32 vcc, 0, v18
	s_addc_u32 s10, s9, 0
	s_and_b32 s17, s10, 0xffff
	v_cndmask_b32_e32 v19, 0, v19, vcc
	v_mul_f32_e32 v21, v94, v19
	v_mul_f32_e32 v42, v42, v19
	v_mul_f32_e32 v20, v92, v19
	v_mul_f32_e32 v92, v96, v19
	v_mul_f32_e32 v94, v98, v19
	v_rndne_f32_e32 v21, v21
	v_mul_f32_e32 v46, v46, v19
	v_mul_f32_e32 v38, v38, v19
	v_mul_f32_e32 v34, v34, v19
	v_rndne_f32_e32 v42, v42
	v_rndne_f32_e32 v20, v20
	v_cvt_i32_f32_e32 v21, v21
	v_rndne_f32_e32 v92, v92
	v_rndne_f32_e32 v94, v94
	v_rndne_f32_e32 v46, v46
	v_cvt_i32_f32_e32 v42, v42
	v_rndne_f32_e32 v38, v38
	v_rndne_f32_e32 v34, v34
	v_cvt_i32_f32_e32 v20, v20
	v_cvt_i32_f32_sdwa v92, v92 dst_sel:WORD_1 dst_unused:UNUSED_PAD src0_sel:DWORD
	v_cvt_i32_f32_e32 v94, v94
	v_cvt_i32_f32_e32 v46, v46
	v_cvt_i32_f32_sdwa v38, v38 dst_sel:WORD_1 dst_unused:UNUSED_PAD src0_sel:DWORD
	v_cvt_i32_f32_e32 v34, v34
	v_lshlrev_b32_e32 v21, 8, v21
	v_lshlrev_b32_e32 v42, 8, v42
	v_and_b32_e32 v21, 0xff00, v21
	v_and_b32_e32 v92, 0xff0000, v92
	v_perm_b32 v20, v94, v20, s35
	v_and_b32_e32 v42, 0xff00, v42
	v_and_b32_e32 v38, 0xff0000, v38
	v_perm_b32 v34, v34, v46, s35
	v_or3_b32 v20, v20, v21, v92
	v_or3_b32 v34, v34, v42, v38
	v_mul_f32_e32 v92, v95, v19
	ds_write2st64_b32 v106, v20, v34 offset1:1
	v_mul_f32_e32 v34, v43, v19
	v_mul_f32_e32 v21, v93, v19
	v_mul_f32_e32 v93, v97, v19
	v_mul_f32_e32 v94, v99, v19
	v_rndne_f32_e32 v92, v92
	v_mul_f32_e32 v20, v47, v19
	v_mul_f32_e32 v38, v39, v19
	v_mul_f32_e32 v35, v35, v19
	v_rndne_f32_e32 v34, v34
	v_rndne_f32_e32 v21, v21
	v_cvt_i32_f32_e32 v92, v92
	v_rndne_f32_e32 v93, v93
	v_rndne_f32_e32 v94, v94
	v_rndne_f32_e32 v20, v20
	v_cvt_i32_f32_e32 v34, v34
	v_rndne_f32_e32 v38, v38
	v_rndne_f32_e32 v35, v35
	v_cvt_i32_f32_e32 v21, v21
	v_cvt_i32_f32_sdwa v93, v93 dst_sel:WORD_1 dst_unused:UNUSED_PAD src0_sel:DWORD
	v_cvt_i32_f32_e32 v94, v94
	v_cvt_i32_f32_e32 v20, v20
	v_cvt_i32_f32_sdwa v38, v38 dst_sel:WORD_1 dst_unused:UNUSED_PAD src0_sel:DWORD
	v_cvt_i32_f32_e32 v35, v35
	v_lshlrev_b32_e32 v92, 8, v92
	v_lshlrev_b32_e32 v34, 8, v34
	v_and_b32_e32 v92, 0xff00, v92
	v_and_b32_e32 v93, 0xff0000, v93
	v_perm_b32 v21, v94, v21, s35
	v_and_b32_e32 v34, 0xff00, v34
	v_and_b32_e32 v38, 0xff0000, v38
	v_perm_b32 v20, v35, v20, s35
	v_or3_b32 v21, v21, v92, v93
	v_or3_b32 v20, v20, v34, v38
	v_add_u32_e32 v34, 16, v106
	v_mul_f32_e32 v86, v86, v19
	ds_write2st64_b32 v34, v21, v20 offset0:4 offset1:5
	v_mul_f32_e32 v21, v44, v19
	v_mul_f32_e32 v84, v84, v19
	v_mul_f32_e32 v88, v88, v19
	v_mul_f32_e32 v90, v90, v19
	v_rndne_f32_e32 v86, v86
	v_mul_f32_e32 v20, v48, v19
	v_mul_f32_e32 v35, v40, v19
	v_mul_f32_e32 v36, v36, v19
	v_rndne_f32_e32 v21, v21
	v_rndne_f32_e32 v84, v84
	v_cvt_i32_f32_e32 v86, v86
	v_rndne_f32_e32 v88, v88
	v_rndne_f32_e32 v90, v90
	v_rndne_f32_e32 v20, v20
	v_cvt_i32_f32_e32 v21, v21
	v_rndne_f32_e32 v35, v35
	v_rndne_f32_e32 v36, v36
	v_cvt_i32_f32_e32 v84, v84
	v_cvt_i32_f32_sdwa v88, v88 dst_sel:WORD_1 dst_unused:UNUSED_PAD src0_sel:DWORD
	v_cvt_i32_f32_e32 v90, v90
	v_cvt_i32_f32_e32 v20, v20
	v_cvt_i32_f32_sdwa v35, v35 dst_sel:WORD_1 dst_unused:UNUSED_PAD src0_sel:DWORD
	v_cvt_i32_f32_e32 v36, v36
	v_lshlrev_b32_e32 v86, 8, v86
	v_lshlrev_b32_e32 v21, 8, v21
	v_and_b32_e32 v86, 0xff00, v86
	v_and_b32_e32 v88, 0xff0000, v88
	v_perm_b32 v84, v90, v84, s35
	v_and_b32_e32 v21, 0xff00, v21
	v_and_b32_e32 v35, 0xff0000, v35
	v_perm_b32 v20, v36, v20, s35
	v_or3_b32 v84, v84, v86, v88
	v_mul_f32_e32 v86, v87, v19
	v_or3_b32 v20, v20, v21, v35
	v_add_u32_e32 v21, 32, v106
	v_mul_f32_e32 v35, v45, v19
	v_mul_f32_e32 v85, v85, v19
	v_mul_f32_e32 v87, v89, v19
	v_mul_f32_e32 v88, v91, v19
	v_rndne_f32_e32 v86, v86
	ds_write2st64_b32 v21, v84, v20 offset0:8 offset1:9
	v_mul_f32_e32 v20, v49, v19
	v_mul_f32_e32 v36, v41, v19
	v_mul_f32_e32 v37, v37, v19
	v_rndne_f32_e32 v35, v35
	v_rndne_f32_e32 v85, v85
	v_cvt_i32_f32_e32 v86, v86
	v_rndne_f32_e32 v87, v87
	v_rndne_f32_e32 v88, v88
	v_rndne_f32_e32 v20, v20
	v_cvt_i32_f32_e32 v35, v35
	v_rndne_f32_e32 v36, v36
	v_rndne_f32_e32 v37, v37
	v_cvt_i32_f32_e32 v85, v85
	v_cvt_i32_f32_sdwa v87, v87 dst_sel:WORD_1 dst_unused:UNUSED_PAD src0_sel:DWORD
	v_cvt_i32_f32_e32 v88, v88
	v_cvt_i32_f32_e32 v20, v20
	v_cvt_i32_f32_sdwa v36, v36 dst_sel:WORD_1 dst_unused:UNUSED_PAD src0_sel:DWORD
	v_cvt_i32_f32_e32 v37, v37
	v_lshlrev_b32_e32 v86, 8, v86
	v_lshlrev_b32_e32 v35, 8, v35
	v_and_b32_e32 v86, 0xff00, v86
	v_and_b32_e32 v87, 0xff0000, v87
	v_perm_b32 v85, v88, v85, s35
	v_and_b32_e32 v35, 0xff00, v35
	v_and_b32_e32 v36, 0xff0000, v36
	v_perm_b32 v20, v37, v20, s35
	v_or3_b32 v85, v85, v86, v87
	v_or3_b32 v20, v20, v35, v36
	v_add_u32_e32 v35, 48, v106
	v_mul_f32_e32 v26, v26, v19
	v_mul_f32_e32 v10, v10, v19
	ds_write2st64_b32 v35, v85, v20 offset0:12 offset1:13
	v_mul_f32_e32 v20, v30, v19
	v_mul_f32_e32 v30, v100, v19
	v_mul_f32_e32 v36, v102, v19
	v_rndne_f32_e32 v26, v26
	v_mul_f32_e32 v14, v14, v19
	v_mul_f32_e32 v6, v6, v19
	v_mul_f32_e32 v2, v2, v19
	v_rndne_f32_e32 v10, v10
	v_rndne_f32_e32 v20, v20
	v_cvt_i32_f32_e32 v26, v26
	v_rndne_f32_e32 v30, v30
	v_rndne_f32_e32 v36, v36
	v_rndne_f32_e32 v14, v14
	v_cvt_i32_f32_e32 v10, v10
	v_rndne_f32_e32 v6, v6
	v_rndne_f32_e32 v2, v2
	v_cvt_i32_f32_e32 v20, v20
	v_cvt_i32_f32_sdwa v30, v30 dst_sel:WORD_1 dst_unused:UNUSED_PAD src0_sel:DWORD
	v_cvt_i32_f32_e32 v36, v36
	v_cvt_i32_f32_e32 v14, v14
	v_cvt_i32_f32_sdwa v6, v6 dst_sel:WORD_1 dst_unused:UNUSED_PAD src0_sel:DWORD
	v_cvt_i32_f32_e32 v2, v2
	v_lshlrev_b32_e32 v26, 8, v26
	v_lshlrev_b32_e32 v10, 8, v10
	v_and_b32_e32 v26, 0xff00, v26
	v_and_b32_e32 v30, 0xff0000, v30
	v_perm_b32 v20, v36, v20, s35
	v_and_b32_e32 v10, 0xff00, v10
	v_and_b32_e32 v6, 0xff0000, v6
	v_perm_b32 v2, v2, v14, s35
	v_or3_b32 v20, v20, v26, v30
	v_mul_f32_e32 v27, v27, v19
	v_or3_b32 v2, v2, v10, v6
	v_mul_f32_e32 v6, v11, v19
	v_mul_f32_e32 v26, v31, v19
	v_mul_f32_e32 v30, v101, v19
	v_mul_f32_e32 v31, v103, v19
	v_rndne_f32_e32 v27, v27
	ds_write2st64_b32 v106, v20, v2 offset0:2 offset1:3
	v_mul_f32_e32 v2, v15, v19
	v_mul_f32_e32 v7, v7, v19
	v_mul_f32_e32 v3, v3, v19
	v_rndne_f32_e32 v6, v6
	v_rndne_f32_e32 v26, v26
	v_cvt_i32_f32_e32 v27, v27
	v_rndne_f32_e32 v30, v30
	v_rndne_f32_e32 v31, v31
	v_rndne_f32_e32 v2, v2
	v_cvt_i32_f32_e32 v6, v6
	v_rndne_f32_e32 v7, v7
	v_rndne_f32_e32 v3, v3
	v_cvt_i32_f32_e32 v26, v26
	v_cvt_i32_f32_sdwa v30, v30 dst_sel:WORD_1 dst_unused:UNUSED_PAD src0_sel:DWORD
	v_cvt_i32_f32_e32 v31, v31
	v_cvt_i32_f32_e32 v2, v2
	v_cvt_i32_f32_sdwa v7, v7 dst_sel:WORD_1 dst_unused:UNUSED_PAD src0_sel:DWORD
	v_cvt_i32_f32_e32 v3, v3
	v_lshlrev_b32_e32 v27, 8, v27
	v_lshlrev_b32_e32 v6, 8, v6
	v_and_b32_e32 v27, 0xff00, v27
	v_and_b32_e32 v30, 0xff0000, v30
	v_perm_b32 v26, v31, v26, s35
	v_and_b32_e32 v6, 0xff00, v6
	v_and_b32_e32 v7, 0xff0000, v7
	v_perm_b32 v2, v3, v2, s35
	v_or3_b32 v26, v26, v27, v30
	v_mul_f32_e32 v28, v28, v19
	v_or3_b32 v2, v2, v6, v7
	v_mul_f32_e32 v3, v12, v19
	v_mul_f32_e32 v27, v32, v19
	v_mul_f32_e32 v24, v24, v19
	v_mul_f32_e32 v22, v22, v19
	v_rndne_f32_e32 v28, v28
	ds_write2st64_b32 v34, v26, v2 offset0:6 offset1:7
	v_mul_f32_e32 v2, v16, v19
	v_mul_f32_e32 v6, v8, v19
	v_mul_f32_e32 v4, v4, v19
	v_rndne_f32_e32 v3, v3
	v_rndne_f32_e32 v27, v27
	v_cvt_i32_f32_e32 v28, v28
	v_rndne_f32_e32 v24, v24
	v_rndne_f32_e32 v22, v22
	v_rndne_f32_e32 v2, v2
	v_cvt_i32_f32_e32 v3, v3
	v_rndne_f32_e32 v6, v6
	v_rndne_f32_e32 v4, v4
	v_cvt_i32_f32_e32 v27, v27
	v_cvt_i32_f32_sdwa v24, v24 dst_sel:WORD_1 dst_unused:UNUSED_PAD src0_sel:DWORD
	v_cvt_i32_f32_e32 v22, v22
	v_cvt_i32_f32_e32 v2, v2
	v_cvt_i32_f32_sdwa v6, v6 dst_sel:WORD_1 dst_unused:UNUSED_PAD src0_sel:DWORD
	v_cvt_i32_f32_e32 v4, v4
	v_lshlrev_b32_e32 v28, 8, v28
	v_lshlrev_b32_e32 v3, 8, v3
	v_and_b32_e32 v28, 0xff00, v28
	v_and_b32_e32 v24, 0xff0000, v24
	v_perm_b32 v22, v22, v27, s35
	v_and_b32_e32 v3, 0xff00, v3
	v_and_b32_e32 v6, 0xff0000, v6
	v_perm_b32 v2, v4, v2, s35
	v_or3_b32 v22, v22, v28, v24
	v_mul_f32_e32 v27, v29, v19
	v_or3_b32 v2, v2, v3, v6
	v_mul_f32_e32 v3, v13, v19
	v_mul_f32_e32 v24, v33, v19
	v_mul_f32_e32 v25, v25, v19
	v_mul_f32_e32 v23, v23, v19
	v_rndne_f32_e32 v27, v27
	ds_write2st64_b32 v21, v22, v2 offset0:10 offset1:11
	v_mul_f32_e32 v2, v17, v19
	v_mul_f32_e32 v4, v9, v19
	v_mul_f32_e32 v5, v5, v19
	v_rndne_f32_e32 v3, v3
	v_rndne_f32_e32 v24, v24
	v_cvt_i32_f32_e32 v27, v27
	v_rndne_f32_e32 v25, v25
	v_rndne_f32_e32 v23, v23
	v_rndne_f32_e32 v2, v2
	v_cvt_i32_f32_e32 v3, v3
	v_rndne_f32_e32 v4, v4
	v_rndne_f32_e32 v5, v5
	v_cvt_i32_f32_e32 v24, v24
	v_cvt_i32_f32_sdwa v25, v25 dst_sel:WORD_1 dst_unused:UNUSED_PAD src0_sel:DWORD
	v_cvt_i32_f32_e32 v23, v23
	v_cvt_i32_f32_e32 v2, v2
	v_cvt_i32_f32_sdwa v4, v4 dst_sel:WORD_1 dst_unused:UNUSED_PAD src0_sel:DWORD
	v_cvt_i32_f32_e32 v5, v5
	v_lshlrev_b32_e32 v27, 8, v27
	v_lshlrev_b32_e32 v3, 8, v3
	v_and_b32_e32 v27, 0xff00, v27
	v_and_b32_e32 v25, 0xff0000, v25
	v_perm_b32 v23, v23, v24, s35
	v_and_b32_e32 v3, 0xff00, v3
	v_and_b32_e32 v4, 0xff0000, v4
	v_perm_b32 v2, v5, v2, s35
	v_or3_b32 v23, v23, v27, v25
	v_or3_b32 v2, v2, v3, v4
	ds_write2st64_b32 v35, v23, v2 offset0:14 offset1:15
	s_waitcnt lgkmcnt(0)
	s_barrier
	ds_read_b128 v[2:5], v109
	ds_read_b128 v[6:9], v109 offset:256
	ds_read_b128 v[10:13], v109 offset:512
	ds_read_b128 v[14:17], v109 offset:768
	v_add_u32_e32 v19, s22, v107
	v_lshl_or_b32 v19, v19, 10, v108
	s_waitcnt lgkmcnt(3)
	buffer_store_dwordx4 v[2:5], v19, s[16:19], 0 offen sc1
	s_waitcnt lgkmcnt(2)
	buffer_store_dwordx4 v[6:9], v19, s[16:19], 0 offen offset:256 sc1
	s_waitcnt lgkmcnt(1)
	buffer_store_dwordx4 v[10:13], v19, s[16:19], 0 offen offset:512 sc1
	s_waitcnt lgkmcnt(0)
	buffer_store_dwordx4 v[14:17], v19, s[16:19], 0 offen offset:768 sc1
	s_and_saveexec_b64 s[10:11], s[4:5]
	s_cbranch_execz .LBB0_1207
	s_lshr_b32 s16, s22, 3
	s_add_u32 s8, s8, s16
	v_mul_f32_e32 v2, 0x3c010204, v18
	s_addc_u32 s9, s9, 0
	v_cndmask_b32_e32 v2, 1.0, v2, vcc
	global_store_dword v237, v2, s[8:9] offset:704 sc1
	s_branch .LBB0_1207
